# SGU tasks share the 16 KiB V^T tile through LDS (each wave brings in 2 KiB by LDS-DMA instead of loading all 16 KiB itself)
# speedup vs baseline: 1.0180x; 1.0051x over previous
.Lsp3_e0:
	s_cmpk_ge_u32 s63, 0xc0
	s_cbranch_scc1 .Lsp3_e2
	v_and_b32_e32 v125, 63, v206
	v_lshrrev_b32_e32 v124, 6, v206
	v_and_b32_e32 v120, 15, v125
	v_readfirstlane_b32 s40, v124
	v_lshrrev_b32_e32 v121, 4, v125
	s_lshr_b32 s41, s63, 2
	s_and_b32 s42, s63, 3
	v_lshlrev_b32_e32 v122, 8, v120
	v_lshl_add_u32 v122, v121, 4, v122
	s_lshl_b32 s43, s36, 2
	s_add_u32 s43, s43, s42
	s_lshl_b32 s100, s43, 7
	s_lshl_b32 s101, s40, 4
	s_add_u32 s100, s100, s101
	s_lshl_b32 s100, s100, 8
	s_add_u32 s100, s100, 0x2dc0000
	s_add_u32 s44, s96, s100
	s_addc_u32 s45, s97, 0
	global_load_dwordx4 v[4:7], v122, s[44:45]
	global_load_dwordx4 v[8:11], v122, s[44:45] offset:64
	global_load_dwordx4 v[12:15], v122, s[44:45] offset:128
	global_load_dwordx4 v[16:19], v122, s[44:45] offset:192
	s_lshl_b32 s100, s41, 8
	s_lshl_b32 s101, s42, 6
	s_add_u32 s100, s100, s101
	s_lshl_b32 s100, s100, 8
	s_add_u32 s100, s100, 0xc784000
	s_add_u32 s46, s96, s100
	s_addc_u32 s47, s97, 0
	s_and_b32 s100, s40, 3
	s_lshl_b32 s100, s100, 2
	v_add_u32_e32 v126, s100, v121
	v_xor_b32_e32 v126, v126, v120
	v_lshlrev_b32_e32 v126, 4, v126
	v_lshl_add_u32 v126, v121, 8, v126
	s_lshl_b32 s101, s40, 10
	s_add_u32 s46, s46, s101
	s_addc_u32 s47, s47, 0
	s_add_u32 m0, s101, 0x23010
	s_nop 0
	global_load_lds_dwordx4 v126, s[46:47]
	s_add_u32 s46, s46, 0x2000
	s_addc_u32 s47, s47, 0
	s_add_u32 m0, s101, 0x25010
	s_nop 0
	global_load_lds_dwordx4 v126, s[46:47]
	v_add_u32_e32 v127, 0, v121
	v_xor_b32_e32 v127, v127, v120
	v_lshlrev_b32_e32 v127, 4, v127
	v_lshl_add_u32 v127, v120, 8, v127
	v_add_u32_e32 v127, 0x23010, v127
	v_add_u32_e32 v128, 4, v121
	v_xor_b32_e32 v128, v128, v120
	v_lshlrev_b32_e32 v128, 4, v128
	v_lshl_add_u32 v128, v120, 8, v128
	v_add_u32_e32 v128, 0x23010, v128
	v_add_u32_e32 v129, 8, v121
	v_xor_b32_e32 v129, v129, v120
	v_lshlrev_b32_e32 v129, 4, v129
	v_lshl_add_u32 v129, v120, 8, v129
	v_add_u32_e32 v129, 0x23010, v129
	v_add_u32_e32 v130, 12, v121
	v_xor_b32_e32 v130, v130, v120
	v_lshlrev_b32_e32 v130, 4, v130
	v_lshl_add_u32 v130, v120, 8, v130
	v_add_u32_e32 v130, 0x23010, v130
	v_readlane_b32 s48, v237, 33
	v_readlane_b32 s49, v237, 34
	s_lshl_b32 s100, s43, 9
	s_lshl_b32 s101, s40, 6
	s_add_u32 s100, s100, s101
	s_add_u32 s48, s48, s100
	s_addc_u32 s49, s49, 0
	v_lshlrev_b32_e32 v125, 4, v121
	s_nop 0
	global_load_dwordx4 v[100:103], v125, s[48:49]
	s_lshl_b32 s100, s41, 7
	s_lshl_b32 s101, s40, 4
	s_add_u32 s100, s100, s101
	s_mul_i32 s50, s100, 0x2440
	s_lshl_b32 s101, s42, 8
	s_add_u32 s50, s50, s101
	s_add_u32 s50, s50, 0x3a25840
	s_add_u32 s52, s96, s50
	s_addc_u32 s53, s97, 0
	v_mul_u32_u24_e32 v123, 0x9100, v121
	v_lshl_add_u32 v123, v120, 2, v123
	global_load_dword v104, v123, s[52:53]
	global_load_dword v105, v123, s[52:53] offset:64
	global_load_dword v106, v123, s[52:53] offset:128
	global_load_dword v107, v123, s[52:53] offset:192
	v_add_u32_e32 v125, 0x2440, v123
	global_load_dword v108, v125, s[52:53]
	global_load_dword v109, v125, s[52:53] offset:64
	global_load_dword v110, v125, s[52:53] offset:128
	global_load_dword v111, v125, s[52:53] offset:192
	v_add_u32_e32 v125, 0x4880, v123
	global_load_dword v112, v125, s[52:53]
	global_load_dword v113, v125, s[52:53] offset:64
	global_load_dword v114, v125, s[52:53] offset:128
	global_load_dword v115, v125, s[52:53] offset:192
	v_add_u32_e32 v125, 0x6cc0, v123
	global_load_dword v116, v125, s[52:53]
	global_load_dword v117, v125, s[52:53] offset:64
	global_load_dword v118, v125, s[52:53] offset:128
	global_load_dword v119, v125, s[52:53] offset:192
	s_lshl_b32 s50, s100, 11
	s_lshl_b32 s101, s42, 7
	s_add_u32 s50, s50, s101
	s_add_u32 s50, s50, 0x7084400
	s_add_u32 s54, s96, s50
	s_addc_u32 s55, s97, 0
	v_lshlrev_b32_e32 v124, 13, v121
	v_lshl_add_u32 v124, v120, 1, v124
	s_waitcnt vmcnt(17)
	s_barrier
	ds_read_b128 v[20:23], v127 offset:0
	ds_read_b128 v[36:39], v128 offset:0
	ds_read_b128 v[52:55], v129 offset:0
	ds_read_b128 v[68:71], v130 offset:0
	ds_read_b128 v[24:27], v127 offset:4096
	ds_read_b128 v[40:43], v128 offset:4096
	ds_read_b128 v[56:59], v129 offset:4096
	ds_read_b128 v[72:75], v130 offset:4096
	ds_read_b128 v[28:31], v127 offset:8192
	ds_read_b128 v[44:47], v128 offset:8192
	ds_read_b128 v[60:63], v129 offset:8192
	ds_read_b128 v[76:79], v130 offset:8192
	s_waitcnt lgkmcnt(8)
	ds_read_b128 v[32:35], v127 offset:12288
	ds_read_b128 v[48:51], v128 offset:12288
	ds_read_b128 v[64:67], v129 offset:12288
	ds_read_b128 v[80:83], v130 offset:12288
	s_waitcnt vmcnt(17) lgkmcnt(0)
	v_mfma_f32_16x16x32_bf16 v[84:87], v[4:7], v[20:23], 0
	v_mfma_f32_16x16x32_bf16 v[88:91], v[4:7], v[24:27], 0
	v_mfma_f32_16x16x32_bf16 v[92:95], v[4:7], v[28:31], 0
	v_mfma_f32_16x16x32_bf16 v[96:99], v[4:7], v[32:35], 0
	v_mfma_f32_16x16x32_bf16 v[84:87], v[8:11], v[36:39], v[84:87]
	v_mfma_f32_16x16x32_bf16 v[88:91], v[8:11], v[40:43], v[88:91]
	v_mfma_f32_16x16x32_bf16 v[92:95], v[8:11], v[44:47], v[92:95]
	v_mfma_f32_16x16x32_bf16 v[96:99], v[8:11], v[48:51], v[96:99]
	v_mfma_f32_16x16x32_bf16 v[84:87], v[12:15], v[52:55], v[84:87]
	v_mfma_f32_16x16x32_bf16 v[88:91], v[12:15], v[56:59], v[88:91]
	v_mfma_f32_16x16x32_bf16 v[92:95], v[12:15], v[60:63], v[92:95]
	v_mfma_f32_16x16x32_bf16 v[96:99], v[12:15], v[64:67], v[96:99]
	v_mfma_f32_16x16x32_bf16 v[84:87], v[16:19], v[68:71], v[84:87]
	v_mfma_f32_16x16x32_bf16 v[88:91], v[16:19], v[72:75], v[88:91]
	v_mfma_f32_16x16x32_bf16 v[92:95], v[16:19], v[76:79], v[92:95]
	v_mfma_f32_16x16x32_bf16 v[96:99], v[16:19], v[80:83], v[96:99]
	s_waitcnt vmcnt(0)
	s_nop 4
	v_mul_f32_e32 v126, 0x3d372713, v104
	v_mul_f32_e32 v126, v104, v126
	v_fma_f32 v126, v104, v126, v104
	v_mul_f32_e32 v126, 0x3f4c422a, v126
	v_add_f32_e32 v126, v126, v126
	v_mul_f32_e32 v126, 0x3fb8aa3b, v126
	v_exp_f32_e32 v126, v126
	v_mul_f32_e32 v127, 0.5, v104
	v_add_f32_e32 v126, 1.0, v126
	v_div_scale_f32 v128, s[100:101], v126, v126, 2.0
	v_rcp_f32_e32 v129, v128
	s_nop 0
	v_fma_f32 v130, -v128, v129, 1.0
	v_fmac_f32_e32 v129, v130, v129
	v_div_scale_f32 v130, vcc, 2.0, v126, 2.0
	v_mul_f32_e32 v131, v130, v129
	v_fma_f32 v132, -v128, v131, v130
	v_fmac_f32_e32 v131, v132, v129
	v_fma_f32 v128, -v128, v131, v130
	v_div_fmas_f32 v128, v128, v129, v131
	v_div_fixup_f32 v126, v128, v126, 2.0
	v_sub_f32_e32 v126, 1.0, v126
	v_add_f32_e32 v126, 1.0, v126
	v_mul_f32_e32 v104, v127, v126
	v_add_f32_e32 v126, v84, v100
	v_mul_f32_e32 v104, v104, v126
	v_bfe_u32 v126, v104, 16, 1
	v_add3_u32 v104, v104, v126, s27
	global_store_short_d16_hi v124, v104, s[54:55]
	v_mul_f32_e32 v126, 0x3d372713, v105
	v_mul_f32_e32 v126, v105, v126
	v_fma_f32 v126, v105, v126, v105
	v_mul_f32_e32 v126, 0x3f4c422a, v126
	v_add_f32_e32 v126, v126, v126
	v_mul_f32_e32 v126, 0x3fb8aa3b, v126
	v_exp_f32_e32 v126, v126
	v_mul_f32_e32 v127, 0.5, v105
	v_add_f32_e32 v126, 1.0, v126
	v_div_scale_f32 v128, s[100:101], v126, v126, 2.0
	v_rcp_f32_e32 v129, v128
	s_nop 0
	v_fma_f32 v130, -v128, v129, 1.0
	v_fmac_f32_e32 v129, v130, v129
	v_div_scale_f32 v130, vcc, 2.0, v126, 2.0
	v_mul_f32_e32 v131, v130, v129
	v_fma_f32 v132, -v128, v131, v130
	v_fmac_f32_e32 v131, v132, v129
	v_fma_f32 v128, -v128, v131, v130
	v_div_fmas_f32 v128, v128, v129, v131
	v_div_fixup_f32 v126, v128, v126, 2.0
	v_sub_f32_e32 v126, 1.0, v126
	v_add_f32_e32 v126, 1.0, v126
	v_mul_f32_e32 v105, v127, v126
	v_add_f32_e32 v126, v88, v100
	v_mul_f32_e32 v105, v105, v126
	v_bfe_u32 v126, v105, 16, 1
	v_add3_u32 v105, v105, v126, s27
	global_store_short_d16_hi v124, v105, s[54:55] offset:32
	v_mul_f32_e32 v126, 0x3d372713, v106
	v_mul_f32_e32 v126, v106, v126
	v_fma_f32 v126, v106, v126, v106
	v_mul_f32_e32 v126, 0x3f4c422a, v126
	v_add_f32_e32 v126, v126, v126
	v_mul_f32_e32 v126, 0x3fb8aa3b, v126
	v_exp_f32_e32 v126, v126
	v_mul_f32_e32 v127, 0.5, v106
	v_add_f32_e32 v126, 1.0, v126
	v_div_scale_f32 v128, s[100:101], v126, v126, 2.0
	v_rcp_f32_e32 v129, v128
	s_nop 0
	v_fma_f32 v130, -v128, v129, 1.0
	v_fmac_f32_e32 v129, v130, v129
	v_div_scale_f32 v130, vcc, 2.0, v126, 2.0
	v_mul_f32_e32 v131, v130, v129
	v_fma_f32 v132, -v128, v131, v130
	v_fmac_f32_e32 v131, v132, v129
	v_fma_f32 v128, -v128, v131, v130
	v_div_fmas_f32 v128, v128, v129, v131
	v_div_fixup_f32 v126, v128, v126, 2.0
	v_sub_f32_e32 v126, 1.0, v126
	v_add_f32_e32 v126, 1.0, v126
	v_mul_f32_e32 v106, v127, v126
	v_add_f32_e32 v126, v92, v100
	v_mul_f32_e32 v106, v106, v126
	v_bfe_u32 v126, v106, 16, 1
	v_add3_u32 v106, v106, v126, s27
	global_store_short_d16_hi v124, v106, s[54:55] offset:64
	v_mul_f32_e32 v126, 0x3d372713, v107
	v_mul_f32_e32 v126, v107, v126
	v_fma_f32 v126, v107, v126, v107
	v_mul_f32_e32 v126, 0x3f4c422a, v126
	v_add_f32_e32 v126, v126, v126
	v_mul_f32_e32 v126, 0x3fb8aa3b, v126
	v_exp_f32_e32 v126, v126
	v_mul_f32_e32 v127, 0.5, v107
	v_add_f32_e32 v126, 1.0, v126
	v_div_scale_f32 v128, s[100:101], v126, v126, 2.0
	v_rcp_f32_e32 v129, v128
	s_nop 0
	v_fma_f32 v130, -v128, v129, 1.0
	v_fmac_f32_e32 v129, v130, v129
	v_div_scale_f32 v130, vcc, 2.0, v126, 2.0
	v_mul_f32_e32 v131, v130, v129
	v_fma_f32 v132, -v128, v131, v130
	v_fmac_f32_e32 v131, v132, v129
	v_fma_f32 v128, -v128, v131, v130
	v_div_fmas_f32 v128, v128, v129, v131
	v_div_fixup_f32 v126, v128, v126, 2.0
	v_sub_f32_e32 v126, 1.0, v126
	v_add_f32_e32 v126, 1.0, v126
	v_mul_f32_e32 v107, v127, v126
	v_add_f32_e32 v126, v96, v100
	v_mul_f32_e32 v107, v107, v126
	v_bfe_u32 v126, v107, 16, 1
	v_add3_u32 v107, v107, v126, s27
	global_store_short_d16_hi v124, v107, s[54:55] offset:96
	v_add_u32_e32 v125, 0x800, v124
	v_mul_f32_e32 v126, 0x3d372713, v108
	v_mul_f32_e32 v126, v108, v126
	v_fma_f32 v126, v108, v126, v108
	v_mul_f32_e32 v126, 0x3f4c422a, v126
	v_add_f32_e32 v126, v126, v126
	v_mul_f32_e32 v126, 0x3fb8aa3b, v126
	v_exp_f32_e32 v126, v126
	v_mul_f32_e32 v127, 0.5, v108
	v_add_f32_e32 v126, 1.0, v126
	v_div_scale_f32 v128, s[100:101], v126, v126, 2.0
	v_rcp_f32_e32 v129, v128
	s_nop 0
	v_fma_f32 v130, -v128, v129, 1.0
	v_fmac_f32_e32 v129, v130, v129
	v_div_scale_f32 v130, vcc, 2.0, v126, 2.0
	v_mul_f32_e32 v131, v130, v129
	v_fma_f32 v132, -v128, v131, v130
	v_fmac_f32_e32 v131, v132, v129
	v_fma_f32 v128, -v128, v131, v130
	v_div_fmas_f32 v128, v128, v129, v131
	v_div_fixup_f32 v126, v128, v126, 2.0
	v_sub_f32_e32 v126, 1.0, v126
	v_add_f32_e32 v126, 1.0, v126
	v_mul_f32_e32 v108, v127, v126
	v_add_f32_e32 v126, v85, v101
	v_mul_f32_e32 v108, v108, v126
	v_bfe_u32 v126, v108, 16, 1
	v_add3_u32 v108, v108, v126, s27
	global_store_short_d16_hi v125, v108, s[54:55]
	v_mul_f32_e32 v126, 0x3d372713, v109
	v_mul_f32_e32 v126, v109, v126
	v_fma_f32 v126, v109, v126, v109
	v_mul_f32_e32 v126, 0x3f4c422a, v126
	v_add_f32_e32 v126, v126, v126
	v_mul_f32_e32 v126, 0x3fb8aa3b, v126
	v_exp_f32_e32 v126, v126
	v_mul_f32_e32 v127, 0.5, v109
	v_add_f32_e32 v126, 1.0, v126
	v_div_scale_f32 v128, s[100:101], v126, v126, 2.0
	v_rcp_f32_e32 v129, v128
	s_nop 0
	v_fma_f32 v130, -v128, v129, 1.0
	v_fmac_f32_e32 v129, v130, v129
	v_div_scale_f32 v130, vcc, 2.0, v126, 2.0
	v_mul_f32_e32 v131, v130, v129
	v_fma_f32 v132, -v128, v131, v130
	v_fmac_f32_e32 v131, v132, v129
	v_fma_f32 v128, -v128, v131, v130
	v_div_fmas_f32 v128, v128, v129, v131
	v_div_fixup_f32 v126, v128, v126, 2.0
	v_sub_f32_e32 v126, 1.0, v126
	v_add_f32_e32 v126, 1.0, v126
	v_mul_f32_e32 v109, v127, v126
	v_add_f32_e32 v126, v89, v101
	v_mul_f32_e32 v109, v109, v126
	v_bfe_u32 v126, v109, 16, 1
	v_add3_u32 v109, v109, v126, s27
	global_store_short_d16_hi v125, v109, s[54:55] offset:32
	v_mul_f32_e32 v126, 0x3d372713, v110
	v_mul_f32_e32 v126, v110, v126
	v_fma_f32 v126, v110, v126, v110
	v_mul_f32_e32 v126, 0x3f4c422a, v126
	v_add_f32_e32 v126, v126, v126
	v_mul_f32_e32 v126, 0x3fb8aa3b, v126
	v_exp_f32_e32 v126, v126
	v_mul_f32_e32 v127, 0.5, v110
	v_add_f32_e32 v126, 1.0, v126
	v_div_scale_f32 v128, s[100:101], v126, v126, 2.0
	v_rcp_f32_e32 v129, v128
	s_nop 0
	v_fma_f32 v130, -v128, v129, 1.0
	v_fmac_f32_e32 v129, v130, v129
	v_div_scale_f32 v130, vcc, 2.0, v126, 2.0
	v_mul_f32_e32 v131, v130, v129
	v_fma_f32 v132, -v128, v131, v130
	v_fmac_f32_e32 v131, v132, v129
	v_fma_f32 v128, -v128, v131, v130
	v_div_fmas_f32 v128, v128, v129, v131
	v_div_fixup_f32 v126, v128, v126, 2.0
	v_sub_f32_e32 v126, 1.0, v126
	v_add_f32_e32 v126, 1.0, v126
	v_mul_f32_e32 v110, v127, v126
	v_add_f32_e32 v126, v93, v101
	v_mul_f32_e32 v110, v110, v126
	v_bfe_u32 v126, v110, 16, 1
	v_add3_u32 v110, v110, v126, s27
	global_store_short_d16_hi v125, v110, s[54:55] offset:64
	v_mul_f32_e32 v126, 0x3d372713, v111
	v_mul_f32_e32 v126, v111, v126
	v_fma_f32 v126, v111, v126, v111
	v_mul_f32_e32 v126, 0x3f4c422a, v126
	v_add_f32_e32 v126, v126, v126
	v_mul_f32_e32 v126, 0x3fb8aa3b, v126
	v_exp_f32_e32 v126, v126
	v_mul_f32_e32 v127, 0.5, v111
	v_add_f32_e32 v126, 1.0, v126
	v_div_scale_f32 v128, s[100:101], v126, v126, 2.0
	v_rcp_f32_e32 v129, v128
	s_nop 0
	v_fma_f32 v130, -v128, v129, 1.0
	v_fmac_f32_e32 v129, v130, v129
	v_div_scale_f32 v130, vcc, 2.0, v126, 2.0
	v_mul_f32_e32 v131, v130, v129
	v_fma_f32 v132, -v128, v131, v130
	v_fmac_f32_e32 v131, v132, v129
	v_fma_f32 v128, -v128, v131, v130
	v_div_fmas_f32 v128, v128, v129, v131
	v_div_fixup_f32 v126, v128, v126, 2.0
	v_sub_f32_e32 v126, 1.0, v126
	v_add_f32_e32 v126, 1.0, v126
	v_mul_f32_e32 v111, v127, v126
	v_add_f32_e32 v126, v97, v101
	v_mul_f32_e32 v111, v111, v126
	v_bfe_u32 v126, v111, 16, 1
	v_add3_u32 v111, v111, v126, s27
	global_store_short_d16_hi v125, v111, s[54:55] offset:96
	v_add_u32_e32 v125, 0x1000, v124
	v_mul_f32_e32 v126, 0x3d372713, v112
	v_mul_f32_e32 v126, v112, v126
	v_fma_f32 v126, v112, v126, v112
	v_mul_f32_e32 v126, 0x3f4c422a, v126
	v_add_f32_e32 v126, v126, v126
	v_mul_f32_e32 v126, 0x3fb8aa3b, v126
	v_exp_f32_e32 v126, v126
	v_mul_f32_e32 v127, 0.5, v112
	v_add_f32_e32 v126, 1.0, v126
	v_div_scale_f32 v128, s[100:101], v126, v126, 2.0
	v_rcp_f32_e32 v129, v128
	s_nop 0
	v_fma_f32 v130, -v128, v129, 1.0
	v_fmac_f32_e32 v129, v130, v129
	v_div_scale_f32 v130, vcc, 2.0, v126, 2.0
	v_mul_f32_e32 v131, v130, v129
	v_fma_f32 v132, -v128, v131, v130
	v_fmac_f32_e32 v131, v132, v129
	v_fma_f32 v128, -v128, v131, v130
	v_div_fmas_f32 v128, v128, v129, v131
	v_div_fixup_f32 v126, v128, v126, 2.0
	v_sub_f32_e32 v126, 1.0, v126
	v_add_f32_e32 v126, 1.0, v126
	v_mul_f32_e32 v112, v127, v126
	v_add_f32_e32 v126, v86, v102
	v_mul_f32_e32 v112, v112, v126
	v_bfe_u32 v126, v112, 16, 1
	v_add3_u32 v112, v112, v126, s27
	global_store_short_d16_hi v125, v112, s[54:55]
	v_mul_f32_e32 v126, 0x3d372713, v113
	v_mul_f32_e32 v126, v113, v126
	v_fma_f32 v126, v113, v126, v113
	v_mul_f32_e32 v126, 0x3f4c422a, v126
	v_add_f32_e32 v126, v126, v126
	v_mul_f32_e32 v126, 0x3fb8aa3b, v126
	v_exp_f32_e32 v126, v126
	v_mul_f32_e32 v127, 0.5, v113
	v_add_f32_e32 v126, 1.0, v126
	v_div_scale_f32 v128, s[100:101], v126, v126, 2.0
	v_rcp_f32_e32 v129, v128
	s_nop 0
	v_fma_f32 v130, -v128, v129, 1.0
	v_fmac_f32_e32 v129, v130, v129
	v_div_scale_f32 v130, vcc, 2.0, v126, 2.0
	v_mul_f32_e32 v131, v130, v129
	v_fma_f32 v132, -v128, v131, v130
	v_fmac_f32_e32 v131, v132, v129
	v_fma_f32 v128, -v128, v131, v130
	v_div_fmas_f32 v128, v128, v129, v131
	v_div_fixup_f32 v126, v128, v126, 2.0
	v_sub_f32_e32 v126, 1.0, v126
	v_add_f32_e32 v126, 1.0, v126
	v_mul_f32_e32 v113, v127, v126
	v_add_f32_e32 v126, v90, v102
	v_mul_f32_e32 v113, v113, v126
	v_bfe_u32 v126, v113, 16, 1
	v_add3_u32 v113, v113, v126, s27
	global_store_short_d16_hi v125, v113, s[54:55] offset:32
	v_mul_f32_e32 v126, 0x3d372713, v114
	v_mul_f32_e32 v126, v114, v126
	v_fma_f32 v126, v114, v126, v114
	v_mul_f32_e32 v126, 0x3f4c422a, v126
	v_add_f32_e32 v126, v126, v126
	v_mul_f32_e32 v126, 0x3fb8aa3b, v126
	v_exp_f32_e32 v126, v126
	v_mul_f32_e32 v127, 0.5, v114
	v_add_f32_e32 v126, 1.0, v126
	v_div_scale_f32 v128, s[100:101], v126, v126, 2.0
	v_rcp_f32_e32 v129, v128
	s_nop 0
	v_fma_f32 v130, -v128, v129, 1.0
	v_fmac_f32_e32 v129, v130, v129
	v_div_scale_f32 v130, vcc, 2.0, v126, 2.0
	v_mul_f32_e32 v131, v130, v129
	v_fma_f32 v132, -v128, v131, v130
	v_fmac_f32_e32 v131, v132, v129
	v_fma_f32 v128, -v128, v131, v130
	v_div_fmas_f32 v128, v128, v129, v131
	v_div_fixup_f32 v126, v128, v126, 2.0
	v_sub_f32_e32 v126, 1.0, v126
	v_add_f32_e32 v126, 1.0, v126
	v_mul_f32_e32 v114, v127, v126
	v_add_f32_e32 v126, v94, v102
	v_mul_f32_e32 v114, v114, v126
	v_bfe_u32 v126, v114, 16, 1
	v_add3_u32 v114, v114, v126, s27
	global_store_short_d16_hi v125, v114, s[54:55] offset:64
	v_mul_f32_e32 v126, 0x3d372713, v115
	v_mul_f32_e32 v126, v115, v126
	v_fma_f32 v126, v115, v126, v115
	v_mul_f32_e32 v126, 0x3f4c422a, v126
	v_add_f32_e32 v126, v126, v126
	v_mul_f32_e32 v126, 0x3fb8aa3b, v126
	v_exp_f32_e32 v126, v126
	v_mul_f32_e32 v127, 0.5, v115
	v_add_f32_e32 v126, 1.0, v126
	v_div_scale_f32 v128, s[100:101], v126, v126, 2.0
	v_rcp_f32_e32 v129, v128
	s_nop 0
	v_fma_f32 v130, -v128, v129, 1.0
	v_fmac_f32_e32 v129, v130, v129
	v_div_scale_f32 v130, vcc, 2.0, v126, 2.0
	v_mul_f32_e32 v131, v130, v129
	v_fma_f32 v132, -v128, v131, v130
	v_fmac_f32_e32 v131, v132, v129
	v_fma_f32 v128, -v128, v131, v130
	v_div_fmas_f32 v128, v128, v129, v131
	v_div_fixup_f32 v126, v128, v126, 2.0
	v_sub_f32_e32 v126, 1.0, v126
	v_add_f32_e32 v126, 1.0, v126
	v_mul_f32_e32 v115, v127, v126
	v_add_f32_e32 v126, v98, v102
	v_mul_f32_e32 v115, v115, v126
	v_bfe_u32 v126, v115, 16, 1
	v_add3_u32 v115, v115, v126, s27
	global_store_short_d16_hi v125, v115, s[54:55] offset:96
	v_add_u32_e32 v125, 0x1800, v124
	v_mul_f32_e32 v126, 0x3d372713, v116
	v_mul_f32_e32 v126, v116, v126
	v_fma_f32 v126, v116, v126, v116
	v_mul_f32_e32 v126, 0x3f4c422a, v126
	v_add_f32_e32 v126, v126, v126
	v_mul_f32_e32 v126, 0x3fb8aa3b, v126
	v_exp_f32_e32 v126, v126
	v_mul_f32_e32 v127, 0.5, v116
	v_add_f32_e32 v126, 1.0, v126
	v_div_scale_f32 v128, s[100:101], v126, v126, 2.0
	v_rcp_f32_e32 v129, v128
	s_nop 0
	v_fma_f32 v130, -v128, v129, 1.0
	v_fmac_f32_e32 v129, v130, v129
	v_div_scale_f32 v130, vcc, 2.0, v126, 2.0
	v_mul_f32_e32 v131, v130, v129
	v_fma_f32 v132, -v128, v131, v130
	v_fmac_f32_e32 v131, v132, v129
	v_fma_f32 v128, -v128, v131, v130
	v_div_fmas_f32 v128, v128, v129, v131
	v_div_fixup_f32 v126, v128, v126, 2.0
	v_sub_f32_e32 v126, 1.0, v126
	v_add_f32_e32 v126, 1.0, v126
	v_mul_f32_e32 v116, v127, v126
	v_add_f32_e32 v126, v87, v103
	v_mul_f32_e32 v116, v116, v126
	v_bfe_u32 v126, v116, 16, 1
	v_add3_u32 v116, v116, v126, s27
	global_store_short_d16_hi v125, v116, s[54:55]
	v_mul_f32_e32 v126, 0x3d372713, v117
	v_mul_f32_e32 v126, v117, v126
	v_fma_f32 v126, v117, v126, v117
	v_mul_f32_e32 v126, 0x3f4c422a, v126
	v_add_f32_e32 v126, v126, v126
	v_mul_f32_e32 v126, 0x3fb8aa3b, v126
	v_exp_f32_e32 v126, v126
	v_mul_f32_e32 v127, 0.5, v117
	v_add_f32_e32 v126, 1.0, v126
	v_div_scale_f32 v128, s[100:101], v126, v126, 2.0
	v_rcp_f32_e32 v129, v128
	s_nop 0
	v_fma_f32 v130, -v128, v129, 1.0
	v_fmac_f32_e32 v129, v130, v129
	v_div_scale_f32 v130, vcc, 2.0, v126, 2.0
	v_mul_f32_e32 v131, v130, v129
	v_fma_f32 v132, -v128, v131, v130
	v_fmac_f32_e32 v131, v132, v129
	v_fma_f32 v128, -v128, v131, v130
	v_div_fmas_f32 v128, v128, v129, v131
	v_div_fixup_f32 v126, v128, v126, 2.0
	v_sub_f32_e32 v126, 1.0, v126
	v_add_f32_e32 v126, 1.0, v126
	v_mul_f32_e32 v117, v127, v126
	v_add_f32_e32 v126, v91, v103
	v_mul_f32_e32 v117, v117, v126
	v_bfe_u32 v126, v117, 16, 1
	v_add3_u32 v117, v117, v126, s27
	global_store_short_d16_hi v125, v117, s[54:55] offset:32
	v_mul_f32_e32 v126, 0x3d372713, v118
	v_mul_f32_e32 v126, v118, v126
	v_fma_f32 v126, v118, v126, v118
	v_mul_f32_e32 v126, 0x3f4c422a, v126
	v_add_f32_e32 v126, v126, v126
	v_mul_f32_e32 v126, 0x3fb8aa3b, v126
	v_exp_f32_e32 v126, v126
	v_mul_f32_e32 v127, 0.5, v118
	v_add_f32_e32 v126, 1.0, v126
	v_div_scale_f32 v128, s[100:101], v126, v126, 2.0
	v_rcp_f32_e32 v129, v128
	s_nop 0
	v_fma_f32 v130, -v128, v129, 1.0
	v_fmac_f32_e32 v129, v130, v129
	v_div_scale_f32 v130, vcc, 2.0, v126, 2.0
	v_mul_f32_e32 v131, v130, v129
	v_fma_f32 v132, -v128, v131, v130
	v_fmac_f32_e32 v131, v132, v129
	v_fma_f32 v128, -v128, v131, v130
	v_div_fmas_f32 v128, v128, v129, v131
	v_div_fixup_f32 v126, v128, v126, 2.0
	v_sub_f32_e32 v126, 1.0, v126
	v_add_f32_e32 v126, 1.0, v126
	v_mul_f32_e32 v118, v127, v126
	v_add_f32_e32 v126, v95, v103
	v_mul_f32_e32 v118, v118, v126
	v_bfe_u32 v126, v118, 16, 1
	v_add3_u32 v118, v118, v126, s27
	global_store_short_d16_hi v125, v118, s[54:55] offset:64
	v_mul_f32_e32 v126, 0x3d372713, v119
	v_mul_f32_e32 v126, v119, v126
	v_fma_f32 v126, v119, v126, v119
	v_mul_f32_e32 v126, 0x3f4c422a, v126
	v_add_f32_e32 v126, v126, v126
	v_mul_f32_e32 v126, 0x3fb8aa3b, v126
	v_exp_f32_e32 v126, v126
	v_mul_f32_e32 v127, 0.5, v119
	v_add_f32_e32 v126, 1.0, v126
	v_div_scale_f32 v128, s[100:101], v126, v126, 2.0
	v_rcp_f32_e32 v129, v128
	s_nop 0
	v_fma_f32 v130, -v128, v129, 1.0
	v_fmac_f32_e32 v129, v130, v129
	v_div_scale_f32 v130, vcc, 2.0, v126, 2.0
	v_mul_f32_e32 v131, v130, v129
	v_fma_f32 v132, -v128, v131, v130
	v_fmac_f32_e32 v131, v132, v129
	v_fma_f32 v128, -v128, v131, v130
	v_div_fmas_f32 v128, v128, v129, v131
	v_div_fixup_f32 v126, v128, v126, 2.0
	v_sub_f32_e32 v126, 1.0, v126
	v_add_f32_e32 v126, 1.0, v126
	v_mul_f32_e32 v119, v127, v126
	v_add_f32_e32 v126, v99, v103
	v_mul_f32_e32 v119, v119, v126
	v_bfe_u32 v126, v119, 16, 1
	v_add3_u32 v119, v119, v126, s27
	global_store_short_d16_hi v125, v119, s[54:55] offset:96
	s_branch .Lsp3_e2
